# v78 + SSM workgroups run their tail rmsnorm job before the SSM job
# baseline (speedup 1.0000x reference)
.LBB0_19:
	s_cmp_lt_i32 s26, 1
	s_cselect_b64 s[10:11], -1, 0
	s_cmp_gt_i32 s27, 0
	s_cselect_b64 s[0:1], -1, 0
	s_cmpk_lt_i32 s96, 0x440
	s_cselect_b64 s[4:5], -1, 0
	s_and_b64 s[4:5], s[4:5], s[10:11]
	s_and_b64 s[0:1], s[4:5], s[0:1]
	v_writelane_b32 v254, s96, 37
	s_mov_b32 s13, 0
	s_andn2_b64 vcc, exec, s[0:1]
	v_and_b32_e32 v228, 15, v0
	v_writelane_b32 v254, s26, 38
	s_nop 1
	v_writelane_b32 v254, s27, 39
	s_cbranch_vccnz .LBB0_103
	v_and_b32_e32 v1, 0x3ff, v0
	v_lshlrev_b32_e32 v8, 3, v1
	v_and_b32_e32 v4, 0xf8, v8
	v_mul_u32_u24_e32 v6, 0x41, v4
	v_bfe_u32 v89, v0, 5, 5
	v_lshlrev_b32_e32 v6, 2, v6
	s_add_u32 s0, s78, 0x600000
	v_lshlrev_b32_e32 v7, 2, v89
	v_add_u32_e32 v9, 0, v6
	s_addc_u32 s1, s79, 0
	v_add3_u32 v90, 0, v7, v6
	v_add_u32_e32 v91, v9, v7
	v_or_b32_e32 v7, 0x200, v1
	v_bfe_u32 v2, v0, 4, 6
	v_mov_b32_e32 v3, 0xffff9800
	s_add_u32 s92, s78, 0x580000
	v_lshrrev_b32_e32 v92, 5, v7
	v_and_or_b32 v86, v2, 28, v3
	v_lshlrev_b32_e32 v3, 2, v1
	s_addc_u32 s93, s79, 0
	s_movk_i32 s2, 0xf8
	v_lshlrev_b32_e32 v7, 2, v92
	v_and_b32_e32 v5, 0xfc, v3
	s_add_u32 s94, s78, 0x380000
	v_add3_u32 v93, 0, v7, v6
	v_add_u32_e32 v94, v9, v7
	v_or_b32_e32 v7, 0x600, v1
	v_bitop3_b32 v3, v3, s2, v3 bitop3:0xc
	s_addc_u32 s95, s79, 0
	v_lshrrev_b32_e32 v96, 5, v7
	v_add_u32_e32 v101, 0, v3
	v_lshlrev_b32_e32 v3, 6, v1
	v_readlane_b32 s16, v254, 5
	s_mov_b32 s90, s96
	s_add_u32 s96, s78, 0x180000
	v_lshlrev_b32_e32 v7, 2, v96
	v_and_b32_e32 v3, 64, v3
	v_lshlrev_b32_e32 v66, 2, v5
	v_mov_b32_e32 v67, 0
	v_readlane_b32 s17, v254, 6
	v_readlane_b32 s20, v254, 9
	v_readlane_b32 s21, v254, 10
	s_addc_u32 s97, s79, 0
	v_add_u32_e32 v98, v9, v7
	v_mul_u32_u24_e32 v9, 0x78, v1
	v_add_u32_e32 v102, 0, v3
	v_lshlrev_b32_e32 v3, 4, v1
	v_lshl_add_u64 v[68:69], s[16:17], 0, v[66:67]
	v_lshl_add_u64 v[70:71], s[20:21], 0, v[66:67]
	s_add_u32 s14, s78, 0x80000
	v_mul_u32_u24_e32 v11, 0x88, v1
	v_bfe_u32 v100, v1, 4, 2
	v_and_b32_e32 v66, 0x3f0, v3
	v_add3_u32 v3, v9, v8, 0
	s_movk_i32 s2, 0x4200
	s_addc_u32 s15, s79, 0
	v_add_u32_e32 v103, 0x200, v3
	v_add3_u32 v104, v3, v11, s2
	v_lshl_add_u32 v3, v100, 9, 0
	s_add_u32 s80, s78, 0x800000
	v_bfe_u32 v87, v0, 6, 4
	v_add_u32_e32 v107, 0x2200, v3
	v_lshl_add_u32 v3, v228, 3, 0
	s_addc_u32 s81, s79, 0
	v_add_u32_e32 v108, 0x200, v3
	v_lshl_add_u32 v3, v87, 3, 0
	s_add_u32 s34, s78, 0x1600000
	v_add_u32_e32 v109, 0x4200, v3
	v_mbcnt_lo_u32_b32 v3, -1, 0
	s_addc_u32 s35, s79, 0
	v_add_u32_e32 v99, 0, v8
	s_movk_i32 s4, 0x78
	v_mbcnt_hi_u32_b32 v110, -1, v3
	v_readlane_b32 s18, v254, 7
	v_readlane_b32 s19, v254, 8
	v_readlane_b32 s22, v254, 11
	v_readlane_b32 s23, v254, 12
	v_readlane_b32 s24, v254, 13
	v_readlane_b32 s25, v254, 14
	v_readlane_b32 s26, v254, 15
	v_readlane_b32 s27, v254, 16
	v_readlane_b32 s28, v254, 17
	v_readlane_b32 s29, v254, 18
	v_readlane_b32 s30, v254, 19
	v_readlane_b32 s31, v254, 20
	v_writelane_b32 v254, s0, 40
	v_and_b32_e32 v2, 63, v0
	v_add3_u32 v97, 0, v7, v6
	s_add_u32 s52, s78, 0xe800000
	v_mad_u32_u24 v10, v1, s4, v99
	v_lshl_add_u64 v[6:7], s[78:79], 0, v[66:67]
	s_mov_b64 s[4:5], 0x2a00000
	v_lshlrev_b32_e32 v66, 1, v5
	v_and_b32_e32 v3, 64, v110
	v_writelane_b32 v254, s1, 41
	v_lshl_add_u32 v88, v2, 2, 0
	v_or_b32_e32 v95, 32, v89
	s_addc_u32 s53, s79, 0
	v_cmp_gt_u32_e64 s[0:1], 64, v1
	v_lshl_add_u64 v[72:73], v[6:7], 0, s[4:5]
	v_lshl_add_u64 v[74:75], s[76:77], 0, v[66:67]
	v_add_u32_e32 v105, 0x2200, v99
	v_or_b32_e32 v106, 0xfffffe00, v1
	v_add_u32_e32 v111, 64, v3
	v_xor_b32_e32 v112, 32, v110
	v_xor_b32_e32 v113, 16, v110
	s_mov_b32 s54, 0x3a800000
	s_mov_b32 s2, 0x800000
	v_lshlrev_b32_e32 v76, 2, v2
	v_lshlrev_b32_e32 v78, 1, v4
	s_mov_b32 s91, 0x3fb8aa3b
	s_mov_b32 s82, 0xc2ce8ed0
	s_mov_b32 s55, 0x42b17218
	s_mov_b32 s83, 0xdb629599
	s_mov_b32 s84, 0xf534ddc0
	s_mov_b32 s85, 0xfc2757d1
	s_mov_b32 s86, 0x4e441529
	s_mov_b32 s87, 0xa2f9836e
	s_mov_b32 s88, 0x3fc90fda
	s_mov_b32 s89, 0xbfc90fda
	v_mov_b32_e32 v114, 0x3c0881c4
	v_mov_b32_e32 v115, 0xbab64f3b
	v_add_u32_e32 v116, v10, v11
	v_xor_b32_e32 v117, 8, v110
	v_mov_b32_e32 v118, 0x7f800000
	v_not_b32_e32 v119, 63
	v_not_b32_e32 v120, 31
	v_mov_b32_e32 v121, 0x7fc00000
	s_mov_b64 s[56:57], 0x800
	s_mov_b32 s98, s3
	s_movk_i32 s99, 0x440
	s_cmpk_lg_u32 s3, 0x100
	s_cbranch_scc1 .Lp0_bal_done
	s_mov_b32 s98, 0xfffffc40
	s_cmpk_lt_u32 s90, 0x80
	s_cbranch_scc0 .Lp0_others
	s_addk_i32 s90, 0x3c0
	s_branch .Lp0_bal_done
.Lp0_others:
	s_movk_i32 s98, 0x80
	s_movk_i32 s99, 0x3c0

.LBB0_21:
	s_add_i32 s90, s90, s98
	s_cmp_lt_u32 s90, s99
	s_cbranch_scc0 .LBB0_102
